# attention phase: sample-first/prompt-first workgroup split by batch parity (vcu bit 4) instead of head parity, for contiguous cache-row streaming and 4-way K/V L2 sharing
# baseline (speedup 1.0000x reference)
.LBB0_114:
	s_or_b64 exec, exec, s[0:1]
	v_readlane_b32 s1, v253, 11
	s_and_b32 s0, s1, 1
	v_readlane_b32 s4, v253, 15
	v_readlane_b32 s5, v253, 16
	s_add_u32 s2, s4, 0xb940000
	s_addc_u32 s3, s5, 0
	v_readlane_b32 s6, v253, 17
	v_readlane_b32 s7, v253, 18
	v_readlane_b32 s8, v253, 19
	v_readlane_b32 s9, v253, 20
	v_readlane_b32 s10, v253, 21
	v_readlane_b32 s11, v253, 22
	v_readlane_b32 s12, v253, 23
	v_readlane_b32 s13, v253, 24
	v_readlane_b32 s14, v253, 25
	v_readlane_b32 s15, v253, 26
	v_readlane_b32 s16, v253, 27
	v_readlane_b32 s17, v253, 28
	v_readlane_b32 s18, v253, 29
	v_readlane_b32 s19, v253, 30
	v_writelane_b32 v253, s2, 52
	s_cmp_eq_u32 s0, 0
	v_mov_b32_e32 v4, 0
	v_writelane_b32 v253, s3, 53
	v_writelane_b32 v253, s0, 54
	s_cselect_b64 s[2:3], -1, 0
	v_writelane_b32 v253, s2, 55
	v_lshlrev_b32_e32 v2, 8, v0
	v_mov_b32_e32 v3, v4
	v_writelane_b32 v253, s3, 56
	s_movk_i32 s89, 0x60
	v_readlane_b32 s2, v253, 31
	v_readlane_b32 s3, v253, 32
	s_movk_i32 s87, 0xc0
	s_movk_i32 s88, 0x2000
	v_lshl_add_u64 v[214:215], s[2:3], 0, v[2:3]
	s_add_u32 s2, s84, 0x4200
	s_addc_u32 s3, s85, 0
	v_writelane_b32 v253, s2, 57
	s_mov_b32 s91, 0x10000
	s_movk_i32 s92, 0x100
	v_writelane_b32 v253, s3, 58
	s_add_u32 s2, s84, 0x7400
	s_addc_u32 s3, s85, 0
	v_writelane_b32 v253, s2, 59
	s_mov_b32 s94, 0x20000
	v_mov_b32_e32 v246, 0x358637bd
	v_writelane_b32 v253, s3, 60
	s_add_u32 s2, s84, 0x7500
	s_addc_u32 s3, s85, 0
	v_writelane_b32 v253, s2, 61
	s_cmpk_lt_i32 s1, 0x58
	s_mov_b32 s95, 0x800000
	v_writelane_b32 v253, s3, 62
	s_cselect_b64 s[2:3], -1, 0
	s_add_i32 s0, s1, 0xffffff64
	v_writelane_b32 v253, s2, 63
	s_cmpk_lt_u32 s0, 0x58
	s_mul_i32 s0, s1, 0x60
	v_writelane_b32 v254, s3, 0
	s_cselect_b64 s[2:3], -1, 0
	v_writelane_b32 v254, s2, 1
	v_mov_b32_e32 v247, 0xff800000
	v_mov_b32_e32 v252, 0x18400000
	v_writelane_b32 v254, s3, 2
	v_writelane_b32 v254, s0, 3
	s_addk_i32 s0, 0xc580
	v_writelane_b32 v254, s0, 4
	v_readlane_b32 s0, v253, 12
	s_bfe_u32 s0, s0, 0x10004
	s_cmp_eq_u32 s0, 0
	s_cselect_b64 s[2:3], -1, 0
	v_writelane_b32 v254, s2, 5
	s_cmp_eq_u32 s0, 1
	s_cselect_b64 s[0:1], -1, 0
	v_writelane_b32 v254, s3, 6
	v_writelane_b32 v254, s0, 7
	v_mov_b32_e32 v250, 0x1a500000
	v_mov_b32_e32 v251, 0x1b208000
	v_writelane_b32 v254, s1, 8
	v_readlane_b32 s0, v253, 35
	v_readlane_b32 s14, v253, 49
	v_readlane_b32 s1, v253, 36
	v_readlane_b32 s15, v253, 50
	s_add_u32 s0, s14, 0x4000
	s_addc_u32 s1, s15, 0
	v_writelane_b32 v254, s0, 9
	v_readlane_b32 s12, v253, 47
	v_readlane_b32 s13, v253, 48
	v_writelane_b32 v254, s1, 10
	s_add_u32 s0, s82, 0x8000000
	v_writelane_b32 v254, s0, 11
	s_addc_u32 s0, s83, 0
	v_writelane_b32 v254, s0, 12
	s_add_u32 s0, s12, 16
	v_writelane_b32 v254, s0, 13
	s_addc_u32 s0, s13, 0
	v_writelane_b32 v254, s0, 14
	s_add_i32 s0, 0, 0x24020
	v_writelane_b32 v254, s0, 15
	s_add_i32 s0, 0, 0x24024
	v_writelane_b32 v254, s0, 16
	s_add_i32 s0, 0, 0x21004
	v_writelane_b32 v254, s0, 17
	s_add_i32 s0, 0, 0x21008
	v_writelane_b32 v254, s0, 18
	s_add_i32 s0, 0, 0x2100c
	v_writelane_b32 v254, s0, 19
	s_add_i32 s0, 0, 0x21010
	v_writelane_b32 v254, s0, 20
	s_add_i32 s0, 0, 0x21014
	v_writelane_b32 v254, s0, 21
	s_add_i32 s0, 0, 0x21018
	v_writelane_b32 v254, s0, 22
	s_add_i32 s0, 0, 0x2101c
	v_writelane_b32 v254, s0, 23
	v_cmp_gt_u32_e64 s[0:1], 16, v0
	v_readlane_b32 s4, v253, 39
	v_readlane_b32 s5, v253, 40
	v_writelane_b32 v254, s0, 24
	s_mov_b32 s51, 0x40c000
	s_mov_b32 s70, 0
	v_writelane_b32 v254, s1, 25
	s_mov_b64 s[0:1], 0
	v_writelane_b32 v254, s0, 26
	s_mov_b64 s[12:13], -1
	s_mov_b64 s[96:97], 0x80000
	v_writelane_b32 v254, s1, 27
	s_mov_b32 s1, 0
	v_writelane_b32 v254, s0, 28
	s_mov_b64 s[48:49], 0x7ffff
	s_mov_b64 s[4:5], 0x40000
	v_writelane_b32 v254, s1, 29
	v_writelane_b32 v254, s84, 30
	s_mov_b32 s86, 0x3e0293ee
	s_mov_b32 s90, 0x3dd53b94
	v_writelane_b32 v254, s85, 31
	v_writelane_b32 v254, s80, 32
	s_waitcnt lgkmcnt(0)
	s_barrier
	v_writelane_b32 v254, s81, 33
	v_writelane_b32 v254, s82, 34
	v_writelane_b32 v254, s83, 35
	v_readlane_b32 s2, v253, 37
	v_readlane_b32 s3, v253, 38
	v_readlane_b32 s6, v253, 41
	v_readlane_b32 s7, v253, 42
	v_readlane_b32 s8, v253, 43
	v_readlane_b32 s9, v253, 44
	v_readlane_b32 s10, v253, 45
	v_readlane_b32 s11, v253, 46
	s_branch .LBB0_118
